# S2 attention-B schedule + static s_setprio 1 for waves 4-7 during differential attention
# speedup vs baseline: 1.0145x; 1.0079x over previous
; __device__ __forceinline__ void attn_phase(LAS unsigned char* lds, unsigned char* ws, int l) {
;     ...
;     for (int vb = blockIdx.x; vb < 256; vb += gridDim.x) {
;         const int v2 = (vb & 7) * 32 + (vb >> 3);
;         const int j = v2 & 7, h = (v2 >> 3) & 7, b = v2 >> 6;
;         const bf16_t* base = P + (size_t)b * SEQ * INW;
;         for (int i = 0; i < 2; ++i) { const int qblk = i ? (15 - j) : j;
;             for (int cmb = 0; cmb < 4; ++cmb) { const int mp = cmb >> 1, sub = cmb & 1;
;                 attn_b_unit(lds, P + P_QB + (size_t)((b * 8 + h) * 2 + mp) * SEQ * 128, P + P_KB + (size_t)((b * 8 + h) * 2 + mp) * SEQ * 128, P + P_VB + (size_t)((b * 8 + h) * 2) * SEQ * 128,
;                             O12 + (size_t)b * SEQ * 4096 + mp * 2048 + h * 256, (qblk * 2 + sub) * 128); }
;             __builtin_amdgcn_fence(__ATOMIC_RELEASE, "workgroup"); __syncthreads(); __builtin_amdgcn_fence(__ATOMIC_ACQUIRE, "workgroup");
;             int tid = threadIdx.x; asm volatile("" : "+v"(tid));
;             const int lane = tid & 63, wv = tid >> 6;
;             const float lam_init = 0.8f - 0.6f * expf(-0.3f * (float)l);
.LBB0_247:
	v_readlane_b32 s0, v253, 18
	v_readlane_b32 s1, v253, 19
	s_andn2_b64 vcc, exec, s[0:1]
	s_cbranch_vccnz .LBB0_289
	v_cvt_f32_u32_e32 v0, s40
	s_lshl_b32 s4, s40, 7
	s_lshl_b32 s0, s40, 8
	s_mov_b32 s1, s5
	v_mul_f32_e32 v0, 0xbe99999a, v0
	v_mul_f32_e32 v2, 0x3fb8aa3b, v0
	v_fma_f32 v3, v0, s83, -v2
	v_rndne_f32_e32 v4, v2
	v_fmac_f32_e32 v3, 0x32a5705f, v0
	v_sub_f32_e32 v2, v2, v4
	v_add_f32_e32 v2, v2, v3
	v_cvt_i32_f32_e32 v4, v4
	v_exp_f32_e32 v2, v2
	v_cmp_ngt_f32_e32 vcc, s84, v0
	s_lshl_b64 s[6:7], s[4:5], 2
	s_lshl_b64 s[30:31], s[0:1], 2
	v_ldexp_f32 v2, v2, v4
	v_cndmask_b32_e32 v2, 0, v2, vcc
	v_cmp_nlt_f32_e32 vcc, s85, v0
	v_readlane_b32 s4, v254, 46
	s_mov_b32 s27, s2
	v_cndmask_b32_e32 v0, v231, v2, vcc
	v_fmamk_f32 v130, v0, 0xbf19999a, v224
	v_sub_f32_e32 v114, 1.0, v130
	v_mov_b32_e32 v116, v114
	v_mov_b32_e32 v117, v114
	s_mov_b32 s98, 0
	v_readfirstlane_b32 s99, v222
	s_lshr_b32 s99, s99, 8
	s_cmp_eq_u32 s99, 1
	s_cbranch_scc0 .Lprio_skip
	s_setprio 1
.Lprio_skip:
.LBB0_249:
	s_and_b32 s0, s27, 7
	s_lshr_b32 s14, s27, 3
	s_and_b32 s15, s0, 1
	s_lshl_b32 s15, s15, 2
	s_add_i32 s15, s15, s98
	s_lshr_b32 s0, s0, 1
	s_sub_i32 s13, 31, s14
	s_bitcmp1_b32 s98, 0
	s_cselect_b32 s14, s13, s14
	s_lshl_b32 s45, s14, 7
	s_lshl_b32 s20, s0, 4
	s_lshl_b32 s8, s15, 1
	s_or_b32 s40, s8, s20
	s_ashr_i32 s1, s0, 31
	s_ashr_i32 s41, s40, 31
	s_lshl_b64 s[34:35], s[0:1], 12
	s_lshl_b64 s[8:9], s[40:41], 20
	v_readlane_b32 s21, v252, 8
	s_add_u32 s42, s21, s8
	v_readlane_b32 s8, v252, 9
	s_addc_u32 s43, s8, s9
	s_lshl_b64 s[0:1], s[0:1], 25
	s_add_u32 s0, s54, s0
	s_addc_u32 s1, s55, s1
	s_lshl_b32 s8, s15, 9
	s_add_u32 s41, s0, s8
	s_addc_u32 s44, s1, 0
	s_mov_b32 s8, s15
	s_lshl_b32 s0, s8, 1
	s_or_b32 s46, s20, s0
	s_ashr_i32 s47, s46, 31
	s_xor_b32 s93, s45, 0xf00
	s_lshl_b64 s[0:1], s[46:47], 20
	v_readlane_b32 s9, v254, 44
	s_add_u32 s58, s9, s0
	v_readlane_b32 s0, v254, 45
	s_addc_u32 s59, s0, s1
	s_lshl_b32 s0, s8, 9
	v_readlane_b32 s1, v253, 44
	s_add_u32 s66, s1, s0
	v_readlane_b32 s1, v253, 45
	s_addc_u32 s67, s1, 0
	s_add_u32 s8, s54, s0
	s_addc_u32 s9, s55, 0
	s_mov_b64 s[0:1], -1

; __device__ __forceinline__ unsigned pk2(float lo, float hi) { f32x2 v = {lo, hi}; bf16x2_t b = __builtin_convertvector(v, bf16x2_t); return __builtin_bit_cast(unsigned, b); }
; __device__ __forceinline__ float bf_lo(unsigned w) { return __uint_as_float(w << 16); }
; __device__ __forceinline__ float bf_hi(unsigned w) { return __uint_as_float(w & 0xffff0000u); }
; __device__ __forceinline__ void attn_phase(LAS unsigned char* lds, unsigned char* ws, int l) {
;     ...
;             for (int r = 0; r < 32; ++r) { const size_t t = (size_t)b * SEQ + qblk * 256 + wv * 32 + r;
;                 const u32x2 a = *(const u32x2*)(O12 + t * 4096 + h * 256 + 4 * lane), bb = *(const u32x2*)(O12 + t * 4096 + 2048 + h * 256 + 4 * lane);
;                 f32x4 o = (f32x4){bf_lo(a.x), bf_hi(a.x), bf_lo(a.y), bf_hi(a.y)} - (f32x4){bf_lo(bb.x), bf_hi(bb.x), bf_lo(bb.y), bf_hi(bb.y)} * lam;
;                 const float ss = wave_sum(o[0] * o[0] + o[1] * o[1] + o[2] * o[2] + o[3] * o[3]);
;                 const float rs = 1.0f / sqrtf(ss * (1.0f / 256.0f) + SUBLN_EPS);
;                 o = o * rs * g;
;                 u32x2 w; w.x = pk2(o[0], o[1]); w.y = pk2(o[2], o[3]);
;                 *(u32x2*)(OB + t * DM + h * 256 + 4 * lane) = w; }
.LBB0_285:
	v_add_co_u32_e32 v20, vcc, 0x1000, v6
	global_load_dwordx2 v[18:19], v[6:7], off
	s_nop 0
	v_addc_co_u32_e32 v21, vcc, 0, v7, vcc
	global_load_dwordx2 v[20:21], v[20:21], off
	v_xor_b32_e32 v27, 0x80000000, v3
	v_xor_b32_e32 v26, 0x80000000, v2
	s_waitcnt vmcnt(1)
	v_lshlrev_b32_e32 v22, 16, v18
	v_and_b32_e32 v23, 0xffff0000, v18
	v_lshlrev_b32_e32 v18, 16, v19
	v_and_b32_e32 v19, 0xffff0000, v19
	s_waitcnt vmcnt(0)
	v_lshlrev_b32_e32 v24, 16, v20
	v_and_b32_e32 v25, 0xffff0000, v20
	v_lshlrev_b32_e32 v20, 16, v21
	v_and_b32_e32 v21, 0xffff0000, v21
	v_pk_fma_f32 v[18:19], v[26:27], v[20:21], v[18:19]
	v_pk_fma_f32 v[20:21], v[12:13], v[24:25], v[22:23] neg_lo:[1,0,0] neg_hi:[1,0,0]
	v_pk_mul_f32 v[22:23], v[18:19], v[18:19]
	v_mul_f32_e32 v24, v21, v21
	v_fmac_f32_e32 v24, v20, v20
	v_add_f32_e32 v22, v22, v24
	v_add_f32_e32 v22, v23, v22
	ds_bpermute_b32 v23, v0, v22
	s_waitcnt lgkmcnt(0)
	v_add_f32_e32 v22, v22, v23
	ds_bpermute_b32 v23, v14, v22
	s_waitcnt lgkmcnt(0)
	v_add_f32_e32 v22, v22, v23
	ds_bpermute_b32 v23, v15, v22
	s_waitcnt lgkmcnt(0)
	v_add_f32_e32 v22, v22, v23
	ds_bpermute_b32 v23, v16, v22
	s_waitcnt lgkmcnt(0)
	v_add_f32_e32 v22, v22, v23
	ds_bpermute_b32 v23, v17, v22
	s_waitcnt lgkmcnt(0)
	v_add_f32_e32 v22, v22, v23
	ds_bpermute_b32 v23, v131, v22
	s_waitcnt lgkmcnt(0)
	v_add_f32_e32 v22, v22, v23
	v_fmamk_f32 v22, v22, 0x3b800000, v225
	v_cmp_gt_f32_e32 vcc, s91, v22
	v_mul_f32_e32 v23, 0x4f800000, v22
	s_nop 0
	v_cndmask_b32_e32 v22, v22, v23, vcc
	v_sqrt_f32_e32 v23, v22
	s_nop 0
	v_add_u32_e32 v24, -1, v23
	v_fma_f32 v25, -v24, v23, v22
	v_cmp_ge_f32_e64 s[0:1], 0, v25
	v_add_u32_e32 v25, 1, v23
	s_nop 0
	v_cndmask_b32_e64 v24, v23, v24, s[0:1]
	v_fma_f32 v23, -v25, v23, v22
	v_cmp_lt_f32_e64 s[0:1], 0, v23
	s_nop 1
	v_cndmask_b32_e64 v23, v24, v25, s[0:1]
	v_mul_f32_e32 v24, 0x37800000, v23
	v_cndmask_b32_e32 v23, v23, v24, vcc
	v_cmp_class_f32_e32 vcc, v22, v226
	s_nop 1
	v_cndmask_b32_e32 v22, v23, v22, vcc
	v_div_scale_f32 v23, s[0:1], v22, v22, 1.0
	v_rcp_f32_e32 v24, v23
	s_mov_b64 s[0:1], 0x2000
	v_lshl_add_u64 v[6:7], v[6:7], 0, s[0:1]
	v_fma_f32 v25, -v23, v24, 1.0
	v_fmac_f32_e32 v24, v25, v24
	v_div_scale_f32 v25, vcc, 1.0, v22, 1.0
	v_mul_f32_e32 v26, v25, v24
	v_fma_f32 v27, -v23, v26, v25
	v_fmac_f32_e32 v26, v27, v24
	v_fma_f32 v23, -v23, v26, v25
	v_div_fmas_f32 v23, v23, v24, v26
	v_div_fixup_f32 v22, v23, v22, 1.0
	v_pk_mul_f32 v[20:21], v[20:21], v[22:23] op_sel_hi:[1,0]
	v_pk_mul_f32 v[18:19], v[18:19], v[22:23] op_sel_hi:[1,0]
	v_pk_mul_f32 v[20:21], v[10:11], v[20:21]
	v_pk_mul_f32 v[18:19], v[8:9], v[18:19]
	v_cvt_pk_bf16_f32 v20, v20, v21
	v_cvt_pk_bf16_f32 v21, v18, v19
	v_lshl_add_u64 v[18:19], v[4:5], 0, s[36:37]
	s_add_u32 s36, s36, 0x1000
	s_addc_u32 s37, s37, 0
	s_cmp_eq_u32 s36, 0x10000
	global_store_dwordx2 v[18:19], v[20:21], off
	s_cbranch_scc0 .LBB0_285
	s_add_i32 s98, s98, 1
	s_cmp_lt_u32 s98, 4
	s_cbranch_scc1 .LBB0_249
	s_setprio 0
	v_readlane_b32 s48, v255, 6
	v_readlane_b32 s49, v255, 7
	v_readlane_b32 s93, v255, 12
	s_mov_b32 s40, s50
